# attention loop: base addresses folded into K/V pointers once per unit, removing 13 per-tile address VALU/nop slots
# speedup vs baseline: 1.0069x; 1.0057x over previous
; __device__ __forceinline__ void attn_diff32(const bf16_t* __restrict__ Qp, const bf16_t* __restrict__ Kp,
;                                             const bf16_t* __restrict__ Vtp, int ntiles, float negM,
;                                             f32x4 (&o)[2][8], float (&l)[2], char* smem) {
;     ...
;   bf16x8 qf[2][2];
; #pragma unroll
;   for (int qt = 0; qt < 2; ++qt) {
;     const bf16_t* qrow = Qp + (size_t)(qg * 32 + qt * 16 + l15) * 512 + cmap * 64;
; #pragma unroll
;     for (int ks = 0; ks < 2; ++ks) qf[qt][ks] = *(const bf16x8*)(qrow + ks * 32 + quad * 8);
;   }
; #pragma unroll
;   for (int qt = 0; qt < 2; ++qt) {
;     l[qt] = 0.f;
; #pragma unroll
;     for (int dt = 0; dt < 8; ++dt) o[qt][dt] = (f32x4){0.f, 0.f, 0.f, 0.f};
;   }
;   uint4 rk00, rk01, rk10, rk11, rv0, rv1, rv2, rv3;
;   const int lr = tid >> 3, lch = (tid & 7) * 8;
;   const uint32_t koff0 = (uint32_t)(lr * 512 + lch) * 2u, koff1 = (uint32_t)((lr + 32) * 512 + lch) * 2u;
;   const uint32_t voff0 = (uint32_t)(lr * TPB + lch) * 2u, voff1 = (uint32_t)((lr + 32) * TPB + lch) * 2u,
;                  voff2 = (uint32_t)((lr + 64) * TPB + lch) * 2u, voff3 = (uint32_t)((lr + 96) * TPB + lch) * 2u;
;     ...
;   AD_LOAD_K(0)
;   AD_LOAD_V(0)
;   const bf16_t* sKc = sK + cmap * 64 * LSTR;
.LBB0_326:
	v_mov_b32_e32 v34, v160
	v_mov_b32_e32 v21, v145
	v_and_b32_e32 v36, 15, v34
	v_ashrrev_i32_e32 v35, 7, v34
	v_lshrrev_b32_e32 v4, 1, v34
	v_and_or_b32 v6, v4, 32, v36
	v_lshlrev_b32_e32 v4, 6, v35
	v_ashrrev_i32_e32 v5, 31, v4
	v_lshl_add_u64 v[4:5], v[4:5], 1, s[70:71]
	v_and_b32_e32 v20, 48, v34
	v_lshl_add_u64 v[4:5], v[4:5], 0, v[20:21]
	v_lshlrev_b32_e32 v6, 10, v6
	v_mov_b32_e32 v7, v145
	v_lshlrev_b32_e32 v22, 3, v34
	v_lshl_add_u64 v[8:9], v[4:5], 0, v[6:7]
	s_movk_i32 s0, 0x4000
	v_ashrrev_i32_e32 v21, 3, v34
	v_and_b32_e32 v23, 56, v22
	global_load_dwordx4 v[12:15], v[8:9], off
	global_load_dwordx4 v[4:7], v[8:9], off offset:64
	v_add_co_u32_e32 v8, vcc, s0, v8
	v_lshlrev_b32_e32 v37, 1, v23
	v_mul_lo_u32 v25, v21, s10
	v_addc_co_u32_e32 v9, vcc, 0, v9, vcc
	v_lshl_or_b32 v22, v21, 10, v37
	v_or_b32_e32 v23, v25, v23
	global_load_dwordx4 v[16:19], v[8:9], off
	s_nop 0
	global_load_dwordx4 v[8:11], v[8:9], off offset:64
	v_add_u32_e32 v24, 0x8000, v22
	v_lshlrev_b32_e32 v26, 1, v23
	global_load_dwordx4 v[52:55], v22, s[68:69]
	global_load_dwordx4 v[56:59], v22, s[68:69] offset:128
	global_load_dwordx4 v[72:75], v24, s[68:69]
	global_load_dwordx4 v[60:63], v24, s[68:69] offset:128
	v_add_u32_e32 v30, 0x208000, v26
	v_add_u32_e32 v28, 0x104000, v26
	v_add_u32_e32 v32, 0x30c000, v26
	global_load_dwordx4 v[100:103], v26, s[38:39]
	global_load_dwordx4 v[104:107], v28, s[38:39]
	global_load_dwordx4 v[108:111], v30, s[38:39]
	global_load_dwordx4 v[112:115], v32, s[38:39]
	v_mul_lo_u32 v21, v21, s11
	v_add3_u32 v158, 16, v21, v37
	v_lshlrev_b32_e32 v21, 1, v34
	v_and_b32_e32 v34, 3, v34
	v_and_or_b32 v21, v21, 24, v34
	v_add_u32_e32 v20, 16, v20
	s_movk_i32 s0, 0x2800
	v_mad_u64_u32 v[34:35], s[2:3], v35, s0, v[20:21]
	s_add_i32 s2, s72, s18
	s_add_i32 s0, s33, 3
	s_mul_hi_u32 s3, s2, 0x410000
	s_mul_i32 s2, s2, 0x410000
	s_add_u32 s2, s2, 0x9f00080
	v_mov_b32_e32 v27, v145
	v_mov_b32_e32 v29, v145
	v_mov_b32_e32 v31, v145
	v_mov_b32_e32 v33, v145
	s_addc_u32 s3, s3, 0
	v_lshl_add_u64 v[134:135], s[2:3], 0, v[26:27]
	v_lshl_add_u64 v[136:137], s[2:3], 0, v[28:29]
	v_lshl_add_u64 v[138:139], s[2:3], 0, v[30:31]
	v_lshl_add_u64 v[150:151], s[2:3], 0, v[32:33]
	s_add_u32 s2, s34, s19
	v_mov_b32_e32 v23, v145
	v_mov_b32_e32 v25, v145
	v_mul_u32_u24_e32 v35, 0xa0, v36
	v_mul_u32_u24_e32 v21, 0xa0, v21
	s_addc_u32 s3, s35, 0
	v_mov_b32_e32 v92, 0
	v_add_u32_e32 v159, 0x1400, v158
	v_add_u32_e32 v166, 0x2800, v158
	v_add_u32_e32 v167, 0x3c00, v158
	v_lshl_add_u64 v[152:153], s[2:3], 0, v[22:23]
	v_lshl_add_u64 v[154:155], s[2:3], 0, v[24:25]
	v_add_u32_e32 v157, v34, v21
	v_add_u32_e32 v156, v20, v35
	v_mov_b32_e32 v93, v92
	v_mov_b32_e32 v94, v92
	v_mov_b32_e32 v95, v92
	v_mov_b32_e32 v64, v92
	v_mov_b32_e32 v65, v92
	v_mov_b32_e32 v66, v92
	v_mov_b32_e32 v67, v92
	v_mov_b32_e32 v44, v92
	v_mov_b32_e32 v45, v92
	v_mov_b32_e32 v46, v92
	v_mov_b32_e32 v47, v92
	v_mov_b32_e32 v36, v92
	v_mov_b32_e32 v37, v92
	v_mov_b32_e32 v38, v92
	v_mov_b32_e32 v39, v92
	v_mov_b32_e32 v32, v92
	v_mov_b32_e32 v33, v92
	v_mov_b32_e32 v34, v92
	v_mov_b32_e32 v35, v92
	v_mov_b32_e32 v28, v92
	v_mov_b32_e32 v29, v92
	v_mov_b32_e32 v30, v92
	v_mov_b32_e32 v31, v92
	v_mov_b32_e32 v24, v92
	v_mov_b32_e32 v25, v92
	v_mov_b32_e32 v26, v92
	v_mov_b32_e32 v27, v92
	v_mov_b32_e32 v20, v92
	v_mov_b32_e32 v21, v92
	v_mov_b32_e32 v22, v92
	v_mov_b32_e32 v23, v92
	v_mov_b32_e32 v96, v92
	v_mov_b32_e32 v97, v92
	v_mov_b32_e32 v98, v92
	v_mov_b32_e32 v99, v92
	v_mov_b32_e32 v88, v92
	v_mov_b32_e32 v89, v92
	v_mov_b32_e32 v90, v92
	v_mov_b32_e32 v91, v92
	v_mov_b32_e32 v84, v92
	v_mov_b32_e32 v85, v92
	v_mov_b32_e32 v86, v92
	v_mov_b32_e32 v87, v92
	v_mov_b32_e32 v80, v92
	v_mov_b32_e32 v81, v92
	v_mov_b32_e32 v82, v92
	v_mov_b32_e32 v83, v92
	v_mov_b32_e32 v76, v92
	v_mov_b32_e32 v77, v92
	v_mov_b32_e32 v78, v92
	v_mov_b32_e32 v79, v92
	v_mov_b32_e32 v68, v92
	v_mov_b32_e32 v69, v92
	v_mov_b32_e32 v70, v92
	v_mov_b32_e32 v71, v92
	v_mov_b32_e32 v48, v92
	v_mov_b32_e32 v49, v92
	v_mov_b32_e32 v50, v92
	v_mov_b32_e32 v51, v92
	v_mov_b32_e32 v40, v92
	v_mov_b32_e32 v41, v92
	v_mov_b32_e32 v42, v92
	v_mov_b32_e32 v43, v92
	v_mov_b32_e32 v132, v92
	v_mov_b32_e32 v133, v92
	s_mov_b32 s98, s12
	s_mov_b32 s99, 0
	v_lshl_add_u64 v[152:153], s[94:95], 0, v[152:153]
	v_lshl_add_u64 v[154:155], s[94:95], 0, v[154:155]
	v_lshl_add_u64 v[134:135], s[94:95], 0, v[134:135]
	v_lshl_add_u64 v[136:137], s[94:95], 0, v[136:137]
	v_lshl_add_u64 v[138:139], s[94:95], 0, v[138:139]
	v_lshl_add_u64 v[150:151], s[94:95], 0, v[150:151]
	v_lshl_add_u64 v[152:153], v[152:153], 0, s[98:99]
	v_lshl_add_u64 v[154:155], v[154:155], 0, s[98:99]
; __device__ __forceinline__ void attn_diff32(const bf16_t* __restrict__ Qp, const bf16_t* __restrict__ Kp,
;                                             const bf16_t* __restrict__ Vtp, int ntiles, float negM,
;                                             f32x4 (&o)[2][8], float (&l)[2], char* smem) {
;     ...
;   for (int n = 0; n < ntiles; ++n) {
;     __syncthreads();
;     *(uint4*)(sK + (lr) * LSTR + lch) = rk00;
;     *(uint4*)(sK + (lr + 32) * LSTR + lch) = rk01;
;     *(uint4*)(sK + (64 + lr) * LSTR + lch) = rk10;
;     *(uint4*)(sK + (64 + lr + 32) * LSTR + lch) = rk11;
;     *(uint4*)(sVt + (lr) * LSTR + lch) = rv0;
;     *(uint4*)(sVt + (lr + 32) * LSTR + lch) = rv1;
;     *(uint4*)(sVt + (lr + 64) * LSTR + lch) = rv2;
;     *(uint4*)(sVt + (lr + 96) * LSTR + lch) = rv3;
;     __syncthreads();
;     const int knext = (n + 1) * 64;
;     if (n + 1 < ntiles) { AD_LOAD_K(knext) }
;     f32x4 s[2][4];
;     __builtin_amdgcn_s_setprio(1);
; #pragma unroll
;     for (int kt = 0; kt < 4; ++kt) {
;       s[0][kt] = (f32x4){negM, negM, negM, negM};
;       s[1][kt] = (f32x4){negM, negM, negM, negM};
;       const int krow = 32 * (kt >> 1) + (l15 >> 2) * 8 + (kt & 1) * 4 + (l15 & 3);
; #pragma unroll
;       for (int ks = 0; ks < 2; ++ks) {
;         const bf16x8 kf = *(const bf16x8*)(sKc + krow * LSTR + ks * 32 + quad * 8);
;         s[0][kt] = __builtin_amdgcn_mfma_f32_16x16x32_bf16(kf, qf[0][ks], s[0][kt], 0, 0, 0);
;         s[1][kt] = __builtin_amdgcn_mfma_f32_16x16x32_bf16(kf, qf[1][ks], s[1][kt], 0, 0, 0);
;       }
;     }
;     __builtin_amdgcn_s_setprio(0);
;     bf16x8 pf[2][2];
; #pragma unroll
;     for (int qt = 0; qt < 2; ++qt) {
;       float ls = 0.f;
; #pragma unroll
;       for (int kt = 0; kt < 4; ++kt)
; #pragma unroll
;         for (int e = 0; e < 4; ++e) {
;           s[qt][kt][e] = fexp2(s[qt][kt][e]);
;           ls += s[qt][kt][e];
;         }
;       l[qt] += ls;
; #pragma unroll
;       for (int ks2 = 0; ks2 < 2; ++ks2) {
;         union { uint32_t u[4]; bf16x8 v; } pk;
;         pk.u[0] = pack2(s[qt][2 * ks2][0], s[qt][2 * ks2][1]);
;         pk.u[1] = pack2(s[qt][2 * ks2][2], s[qt][2 * ks2][3]);
;         pk.u[2] = pack2(s[qt][2 * ks2 + 1][0], s[qt][2 * ks2 + 1][1]);
;         pk.u[3] = pack2(s[qt][2 * ks2 + 1][2], s[qt][2 * ks2 + 1][3]);
;         pf[qt][ks2] = pk.v;
;       }
;     }
;     if (n + 1 < ntiles) { AD_LOAD_V(knext) }
.LBB0_327:
	s_barrier
	s_waitcnt vmcnt(7)
	ds_write_b128 v158, v[52:55]
	s_waitcnt vmcnt(5)
	ds_write_b128 v159, v[72:75]
	ds_write_b128 v166, v[56:59]
	s_waitcnt vmcnt(4)
	ds_write_b128 v158, v[60:63] offset:15360
	s_waitcnt vmcnt(3)
	ds_write_b128 v158, v[100:103] offset:20480
	s_waitcnt vmcnt(2)
	ds_write_b128 v159, v[104:107] offset:20480
	s_waitcnt vmcnt(1)
	ds_write_b128 v166, v[108:111] offset:20480
	s_waitcnt vmcnt(0)
	ds_write_b128 v167, v[112:115] offset:20480
	s_waitcnt lgkmcnt(0)
	s_barrier
	s_setprio 1
	ds_read_b128 v[186:189], v157
	ds_read_b128 v[190:193], v157 offset:64
	ds_read_b128 v[194:197], v157 offset:640
	ds_read_b128 v[198:201], v157 offset:704
	ds_read_b128 v[202:205], v157 offset:5120
	ds_read_b128 v[128:131], v157 offset:5184
	ds_read_b128 v[242:245], v157 offset:5760
	ds_read_b128 v[246:249], v157 offset:5824
	global_load_dwordx4 v[52:55], v[152:153], off
	global_load_dwordx4 v[56:59], v[152:153], off offset:128
	global_load_dwordx4 v[72:75], v[154:155], off
	global_load_dwordx4 v[60:63], v[154:155], off offset:128
	s_waitcnt lgkmcnt(7)
	v_mfma_f32_16x16x32_bf16 v[108:111], v[186:189], v[12:15], v[0:3]
	v_mfma_f32_16x16x32_bf16 v[100:103], v[186:189], v[16:19], v[0:3]
	s_waitcnt lgkmcnt(6)
	v_mfma_f32_16x16x32_bf16 v[108:111], v[190:193], v[4:7], v[108:111]
	v_mfma_f32_16x16x32_bf16 v[100:103], v[190:193], v[8:11], v[100:103]
	s_waitcnt lgkmcnt(5)
	v_mfma_f32_16x16x32_bf16 v[116:119], v[194:197], v[12:15], v[0:3]
	v_mfma_f32_16x16x32_bf16 v[104:107], v[194:197], v[16:19], v[0:3]
	s_waitcnt lgkmcnt(4)
	v_mfma_f32_16x16x32_bf16 v[116:119], v[198:201], v[4:7], v[116:119]
	v_mfma_f32_16x16x32_bf16 v[104:107], v[198:201], v[8:11], v[104:107]
	s_waitcnt lgkmcnt(3)
	v_mfma_f32_16x16x32_bf16 v[124:127], v[202:205], v[12:15], v[0:3]
	v_mfma_f32_16x16x32_bf16 v[112:115], v[202:205], v[16:19], v[0:3]
	s_waitcnt lgkmcnt(2)
	v_mfma_f32_16x16x32_bf16 v[124:127], v[128:131], v[4:7], v[124:127]
	v_mfma_f32_16x16x32_bf16 v[112:115], v[128:131], v[8:11], v[112:115]
	s_waitcnt lgkmcnt(1)
	v_mfma_f32_16x16x32_bf16 v[182:185], v[242:245], v[12:15], v[0:3]
	v_mfma_f32_16x16x32_bf16 v[120:123], v[242:245], v[16:19], v[0:3]
	s_waitcnt lgkmcnt(0)
	v_mfma_f32_16x16x32_bf16 v[182:185], v[246:249], v[4:7], v[182:185]
	v_mfma_f32_16x16x32_bf16 v[120:123], v[246:249], v[8:11], v[120:123]
	ds_read_b128 v[242:245], v156 offset:20480
	ds_read_b128 v[246:249], v156 offset:23040
	ds_read_b128 v[250:253], v156 offset:25600
	s_setprio 0
	v_exp_f32_e32 v129, v108
	v_exp_f32_e32 v128, v100
	v_exp_f32_e32 v109, v109
	v_exp_f32_e32 v108, v101
	v_exp_f32_e32 v131, v110
	v_exp_f32_e32 v130, v102
	v_exp_f32_e32 v111, v111
	v_exp_f32_e32 v110, v103
	v_exp_f32_e32 v187, v116
	v_exp_f32_e32 v186, v104
	v_pk_add_f32 v[100:101], v[128:129], 0 op_sel_hi:[1,0]
	v_exp_f32_e32 v189, v117
	v_exp_f32_e32 v188, v105
	v_pk_add_f32 v[100:101], v[108:109], v[100:101]
	v_exp_f32_e32 v191, v118
	v_pk_add_f32 v[100:101], v[130:131], v[100:101]
	v_exp_f32_e32 v190, v106
	v_exp_f32_e32 v193, v119
	v_pk_add_f32 v[100:101], v[110:111], v[100:101]
	v_exp_f32_e32 v192, v107
	v_exp_f32_e32 v195, v124
	v_pk_add_f32 v[100:101], v[100:101], v[186:187]
	v_exp_f32_e32 v194, v112
	v_exp_f32_e32 v197, v125
	v_pk_add_f32 v[100:101], v[188:189], v[100:101]
	v_exp_f32_e32 v196, v113
	v_exp_f32_e32 v199, v126
	v_exp_f32_e32 v198, v114
	v_pk_add_f32 v[100:101], v[190:191], v[100:101]
	v_exp_f32_e32 v201, v127
	v_exp_f32_e32 v200, v115
	v_pk_add_f32 v[100:101], v[192:193], v[100:101]
	v_exp_f32_e32 v203, v182
	v_exp_f32_e32 v202, v120
	v_pk_add_f32 v[100:101], v[100:101], v[194:195]
	v_exp_f32_e32 v183, v183
	v_exp_f32_e32 v182, v121
	v_pk_add_f32 v[100:101], v[196:197], v[100:101]
	v_exp_f32_e32 v205, v184
	v_exp_f32_e32 v204, v122
	v_pk_add_f32 v[100:101], v[198:199], v[100:101]
	v_exp_f32_e32 v185, v185
	v_exp_f32_e32 v184, v123
	v_pk_add_f32 v[100:101], v[200:201], v[100:101]
	v_cvt_pk_bf16_f32 v124, v129, v109
	v_pk_add_f32 v[100:101], v[100:101], v[202:203]
	v_cvt_pk_bf16_f32 v128, v128, v108
	v_pk_add_f32 v[100:101], v[182:183], v[100:101]
	v_pk_add_f32 v[100:101], v[204:205], v[100:101]
	v_pk_add_f32 v[100:101], v[184:185], v[100:101]
	v_pk_add_f32 v[132:133], v[132:133], v[100:101]
	v_cvt_pk_bf16_f32 v125, v131, v111
	v_cvt_pk_bf16_f32 v129, v130, v110
	global_load_dwordx4 v[100:103], v[134:135], off
	s_nop 0
	global_load_dwordx4 v[104:107], v[136:137], off
	s_nop 0
	global_load_dwordx4 v[108:111], v[138:139], off
	s_nop 0
	global_load_dwordx4 v[112:115], v[150:151], off
	v_cvt_pk_bf16_f32 v126, v187, v189
	v_cvt_pk_bf16_f32 v127, v191, v193
	v_cvt_pk_bf16_f32 v116, v195, v197
	v_cvt_pk_bf16_f32 v117, v199, v201
	v_cvt_pk_bf16_f32 v118, v203, v183
	v_cvt_pk_bf16_f32 v119, v205, v185
	v_cvt_pk_bf16_f32 v130, v186, v188
	v_cvt_pk_bf16_f32 v131, v190, v192
	v_cvt_pk_bf16_f32 v120, v194, v196
	v_cvt_pk_bf16_f32 v121, v198, v200
	v_cvt_pk_bf16_f32 v122, v202, v182
	v_cvt_pk_bf16_f32 v123, v204, v184
	s_setprio 1
	ds_read_b128 v[182:185], v156 offset:28160
	ds_read_b128 v[186:189], v156 offset:30720
	ds_read_b128 v[190:193], v156 offset:33280
	ds_read_b128 v[194:197], v156 offset:35840
	ds_read_b128 v[198:201], v156 offset:38400
	ds_read_b128 v[202:205], v156 offset:20544
	s_waitcnt lgkmcnt(8)
	v_mfma_f32_16x16x32_bf16 v[40:43], v[242:245], v[124:127], v[40:43]
	v_mfma_f32_16x16x32_bf16 v[20:23], v[242:245], v[128:131], v[20:23]
	ds_read_b128 v[242:245], v156 offset:23104
	v_lshl_add_u64 v[134:135], v[134:135], 0, s[24:25]
	s_waitcnt lgkmcnt(8)
	v_mfma_f32_16x16x32_bf16 v[48:51], v[246:249], v[124:127], v[48:51]
	v_mfma_f32_16x16x32_bf16 v[24:27], v[246:249], v[128:131], v[24:27]
	ds_read_b128 v[246:249], v156 offset:25664
	v_lshl_add_u64 v[136:137], v[136:137], 0, s[24:25]
	s_waitcnt lgkmcnt(8)
; __device__ __forceinline__ void attn_diff32(const bf16_t* __restrict__ Qp, const bf16_t* __restrict__ Kp,
;                                             const bf16_t* __restrict__ Vtp, int ntiles, float negM,
;                                             f32x4 (&o)[2][8], float (&l)[2], char* smem) {
;     ...
;     __syncthreads();
;     *(uint4*)(sK + (lr) * LSTR + lch) = rk00;
;     *(uint4*)(sK + (lr + 32) * LSTR + lch) = rk01;
;     *(uint4*)(sK + (64 + lr) * LSTR + lch) = rk10;
;     *(uint4*)(sK + (64 + lr + 32) * LSTR + lch) = rk11;
;     *(uint4*)(sVt + (lr) * LSTR + lch) = rv0;
;     *(uint4*)(sVt + (lr + 32) * LSTR + lch) = rv1;
;     *(uint4*)(sVt + (lr + 64) * LSTR + lch) = rv2;
;     *(uint4*)(sVt + (lr + 96) * LSTR + lch) = rv3;
;     __syncthreads();
;     const int knext = (n + 1) * 64;
;     if (n + 1 < ntiles) { AD_LOAD_K(knext) }
;     f32x4 s[2][4];
;     __builtin_amdgcn_s_setprio(1);
; #pragma unroll
;     for (int kt = 0; kt < 4; ++kt) {
;       s[0][kt] = (f32x4){negM, negM, negM, negM};
;       s[1][kt] = (f32x4){negM, negM, negM, negM};
;       const int krow = 32 * (kt >> 1) + (l15 >> 2) * 8 + (kt & 1) * 4 + (l15 & 3);
; #pragma unroll
;       for (int ks = 0; ks < 2; ++ks) {
;         const bf16x8 kf = *(const bf16x8*)(sKc + krow * LSTR + ks * 32 + quad * 8);
;         s[0][kt] = __builtin_amdgcn_mfma_f32_16x16x32_bf16(kf, qf[0][ks], s[0][kt], 0, 0, 0);
;         s[1][kt] = __builtin_amdgcn_mfma_f32_16x16x32_bf16(kf, qf[1][ks], s[1][kt], 0, 0, 0);
;       }
;     }
;     ...
; #pragma unroll
;     for (int ks2 = 0; ks2 < 2; ++ks2)
; #pragma unroll
;       for (int dt = 0; dt < 8; ++dt) {
;         const bf16x8 vf = *(const bf16x8*)(sVt + (dt * 16 + l15) * LSTR + 32 * ks2 + quad * 8);
;         o[0][dt] = __builtin_amdgcn_mfma_f32_16x16x32_bf16(vf, pf[0][ks2], o[0][dt], 0, 0, 0);
;         o[1][dt] = __builtin_amdgcn_mfma_f32_16x16x32_bf16(vf, pf[1][ks2], o[1][dt], 0, 0, 0);
;       }
;     __builtin_amdgcn_s_setprio(0);
	v_mfma_f32_16x16x32_bf16 v[68:71], v[250:253], v[124:127], v[68:71]
	v_mfma_f32_16x16x32_bf16 v[28:31], v[250:253], v[128:131], v[28:31]
	ds_read_b128 v[250:253], v156 offset:28224
	v_lshl_add_u64 v[138:139], v[138:139], 0, s[24:25]
	s_waitcnt lgkmcnt(8)
	v_mfma_f32_16x16x32_bf16 v[76:79], v[182:185], v[124:127], v[76:79]
	v_mfma_f32_16x16x32_bf16 v[32:35], v[182:185], v[128:131], v[32:35]
	ds_read_b128 v[182:185], v156 offset:30784
	v_lshl_add_u64 v[150:151], v[150:151], 0, s[24:25]
	s_waitcnt lgkmcnt(8)
	v_mfma_f32_16x16x32_bf16 v[80:83], v[186:189], v[124:127], v[80:83]
	v_mfma_f32_16x16x32_bf16 v[36:39], v[186:189], v[128:131], v[36:39]
	ds_read_b128 v[186:189], v156 offset:33344
	v_lshl_add_u64 v[152:153], v[152:153], 0, s[26:27]
	s_waitcnt lgkmcnt(8)
	v_mfma_f32_16x16x32_bf16 v[84:87], v[190:193], v[124:127], v[84:87]
	v_mfma_f32_16x16x32_bf16 v[44:47], v[190:193], v[128:131], v[44:47]
	ds_read_b128 v[190:193], v156 offset:35904
	v_lshl_add_u64 v[154:155], v[154:155], 0, s[26:27]
	s_waitcnt lgkmcnt(8)
	v_mfma_f32_16x16x32_bf16 v[88:91], v[194:197], v[124:127], v[88:91]
	v_mfma_f32_16x16x32_bf16 v[64:67], v[194:197], v[128:131], v[64:67]
	ds_read_b128 v[194:197], v156 offset:38464
	s_waitcnt lgkmcnt(8)
	v_mfma_f32_16x16x32_bf16 v[96:99], v[198:201], v[124:127], v[96:99]
	v_mfma_f32_16x16x32_bf16 v[92:95], v[198:201], v[128:131], v[92:95]
	s_waitcnt lgkmcnt(7)
	v_mfma_f32_16x16x32_bf16 v[40:43], v[202:205], v[116:119], v[40:43]
	v_mfma_f32_16x16x32_bf16 v[20:23], v[202:205], v[120:123], v[20:23]
	s_waitcnt lgkmcnt(6)
	v_mfma_f32_16x16x32_bf16 v[48:51], v[242:245], v[116:119], v[48:51]
	v_mfma_f32_16x16x32_bf16 v[24:27], v[242:245], v[120:123], v[24:27]
	s_waitcnt lgkmcnt(5)
	v_mfma_f32_16x16x32_bf16 v[68:71], v[246:249], v[116:119], v[68:71]
	v_mfma_f32_16x16x32_bf16 v[28:31], v[246:249], v[120:123], v[28:31]
	s_waitcnt lgkmcnt(4)
	v_mfma_f32_16x16x32_bf16 v[76:79], v[250:253], v[116:119], v[76:79]
	v_mfma_f32_16x16x32_bf16 v[32:35], v[250:253], v[120:123], v[32:35]
	s_waitcnt lgkmcnt(3)
	v_mfma_f32_16x16x32_bf16 v[80:83], v[182:185], v[116:119], v[80:83]
	v_mfma_f32_16x16x32_bf16 v[36:39], v[182:185], v[120:123], v[36:39]
	s_waitcnt lgkmcnt(2)
	v_mfma_f32_16x16x32_bf16 v[84:87], v[186:189], v[116:119], v[84:87]
	v_mfma_f32_16x16x32_bf16 v[44:47], v[186:189], v[120:123], v[44:47]
	s_waitcnt lgkmcnt(1)
	v_mfma_f32_16x16x32_bf16 v[88:91], v[190:193], v[116:119], v[88:91]
	v_mfma_f32_16x16x32_bf16 v[64:67], v[190:193], v[120:123], v[64:67]
	s_waitcnt lgkmcnt(0)
	v_mfma_f32_16x16x32_bf16 v[96:99], v[194:197], v[116:119], v[96:99]
	v_mfma_f32_16x16x32_bf16 v[92:95], v[194:197], v[120:123], v[92:95]
	s_setprio 0
	s_add_i32 s0, s0, -1
	s_cmp_lg_u32 s0, 0
	s_cbranch_scc1 .LBB0_327
	s_barrier
	s_waitcnt vmcnt(7)
	ds_write_b128 v158, v[52:55]
	s_waitcnt vmcnt(5)
	ds_write_b128 v159, v[72:75]
	ds_write_b128 v166, v[56:59]
	s_waitcnt vmcnt(4)
	ds_write_b128 v158, v[60:63] offset:15360
	s_waitcnt vmcnt(3)
	ds_write_b128 v158, v[100:103] offset:20480
	s_waitcnt vmcnt(2)
	ds_write_b128 v159, v[104:107] offset:20480
	s_waitcnt vmcnt(1)
	ds_write_b128 v166, v[108:111] offset:20480
	s_waitcnt vmcnt(0)
	ds_write_b128 v167, v[112:115] offset:20480
	s_waitcnt lgkmcnt(0)
	s_barrier
	s_setprio 1
	ds_read_b128 v[52:55], v157
	ds_read_b128 v[60:63], v157 offset:64
	s_waitcnt lgkmcnt(1)
	v_mfma_f32_16x16x32_bf16 v[56:59], v[52:55], v[12:15], v[0:3]
	ds_read_b128 v[100:103], v157 offset:704
	ds_read_b128 v[108:111], v157 offset:5184
	v_mfma_f32_16x16x32_bf16 v[52:55], v[52:55], v[16:19], v[0:3]
	s_waitcnt lgkmcnt(2)
	v_mfma_f32_16x16x32_bf16 v[56:59], v[60:63], v[4:7], v[56:59]
	v_mfma_f32_16x16x32_bf16 v[52:55], v[60:63], v[8:11], v[52:55]
	ds_read_b128 v[60:63], v157 offset:640
	s_waitcnt lgkmcnt(0)
	v_mfma_f32_16x16x32_bf16 v[72:75], v[60:63], v[12:15], v[0:3]
	v_mfma_f32_16x16x32_bf16 v[60:63], v[60:63], v[16:19], v[0:3]
	v_mfma_f32_16x16x32_bf16 v[72:75], v[100:103], v[4:7], v[72:75]
	v_mfma_f32_16x16x32_bf16 v[60:63], v[100:103], v[8:11], v[60:63]
	ds_read_b128 v[100:103], v157 offset:5120
	s_waitcnt lgkmcnt(0)
	v_mfma_f32_16x16x32_bf16 v[104:107], v[100:103], v[12:15], v[0:3]
	v_mfma_f32_16x16x32_bf16 v[100:103], v[100:103], v[16:19], v[0:3]
	v_mfma_f32_16x16x32_bf16 v[104:107], v[108:111], v[4:7], v[104:107]
	v_mfma_f32_16x16x32_bf16 v[100:103], v[108:111], v[8:11], v[100:103]
	ds_read_b128 v[108:111], v157 offset:5760
	s_waitcnt lgkmcnt(0)
	v_mfma_f32_16x16x32_bf16 v[12:15], v[108:111], v[12:15], v[0:3]
	v_mfma_f32_16x16x32_bf16 v[16:19], v[108:111], v[16:19], v[0:3]
	ds_read_b128 v[108:111], v157 offset:5824
	s_waitcnt lgkmcnt(0)
; __device__ __forceinline__ float fexp2(float x) { return __builtin_amdgcn_exp2f(x); }
; __device__ __forceinline__ void attn_diff32(const bf16_t* __restrict__ Qp, const bf16_t* __restrict__ Kp,
;                                             const bf16_t* __restrict__ Vtp, int ntiles, float negM,
;                                             f32x4 (&o)[2][8], float (&l)[2], char* smem) {
;     ...
;     bf16x8 pf[2][2];
; #pragma unroll
;     for (int qt = 0; qt < 2; ++qt) {
;       float ls = 0.f;
; #pragma unroll
;       for (int kt = 0; kt < 4; ++kt)
; #pragma unroll
;         for (int e = 0; e < 4; ++e) {
;           s[qt][kt][e] = fexp2(s[qt][kt][e]);
;           ls += s[qt][kt][e];
;         }
;       l[qt] += ls;
; #pragma unroll
;       for (int ks2 = 0; ks2 < 2; ++ks2) {
;         union { uint32_t u[4]; bf16x8 v; } pk;
;         pk.u[0] = pack2(s[qt][2 * ks2][0], s[qt][2 * ks2][1]);
;         pk.u[1] = pack2(s[qt][2 * ks2][2], s[qt][2 * ks2][3]);
;         pk.u[2] = pack2(s[qt][2 * ks2 + 1][0], s[qt][2 * ks2 + 1][1]);
;         pk.u[3] = pack2(s[qt][2 * ks2 + 1][2], s[qt][2 * ks2 + 1][3]);
;         pf[qt][ks2] = pk.v;
;       }
;     }
;     if (n + 1 < ntiles) { AD_LOAD_V(knext) }
;     __builtin_amdgcn_s_setprio(1);
; #pragma unroll
;     for (int ks2 = 0; ks2 < 2; ++ks2)
; #pragma unroll
;       for (int dt = 0; dt < 8; ++dt) {
;         const bf16x8 vf = *(const bf16x8*)(sVt + (dt * 16 + l15) * LSTR + 32 * ks2 + quad * 8);
;         o[0][dt] = __builtin_amdgcn_mfma_f32_16x16x32_bf16(vf, pf[0][ks2], o[0][dt], 0, 0, 0);
;         o[1][dt] = __builtin_amdgcn_mfma_f32_16x16x32_bf16(vf, pf[1][ks2], o[1][dt], 0, 0, 0);
;       }
;     __builtin_amdgcn_s_setprio(0);
	v_mfma_f32_16x16x32_bf16 v[4:7], v[108:111], v[4:7], v[12:15]
	v_mfma_f32_16x16x32_bf16 v[8:11], v[108:111], v[8:11], v[16:19]
	s_setprio 0
	s_nop 1
	v_exp_f32_e32 v12, v56
	v_exp_f32_e32 v13, v57
	v_exp_f32_e32 v14, v58
	v_exp_f32_e32 v15, v59
	v_add_f32_e32 v16, 0, v12
	v_exp_f32_e32 v17, v72
	v_add_f32_e32 v16, v13, v16
	v_exp_f32_e32 v18, v73
	v_add_f32_e32 v16, v14, v16
	v_exp_f32_e32 v19, v74
	v_add_f32_e32 v16, v15, v16
	v_exp_f32_e32 v56, v75
	v_add_f32_e32 v16, v16, v17
	v_exp_f32_e32 v57, v104
	v_add_f32_e32 v16, v18, v16
	v_exp_f32_e32 v58, v105
	v_add_f32_e32 v16, v19, v16
	v_exp_f32_e32 v59, v106
	v_add_f32_e32 v16, v56, v16
	v_exp_f32_e32 v72, v107
	v_add_f32_e32 v16, v16, v57
	v_exp_f32_e32 v73, v4
	v_add_f32_e32 v16, v58, v16
	v_exp_f32_e32 v74, v5
	v_add_f32_e32 v16, v59, v16
	v_exp_f32_e32 v75, v6
	v_add_f32_e32 v16, v72, v16
	v_exp_f32_e32 v104, v7
	v_add_f32_e32 v4, v16, v73
	v_exp_f32_e32 v16, v52
	v_add_f32_e32 v4, v74, v4
	v_exp_f32_e32 v52, v53
	v_add_f32_e32 v4, v75, v4
	v_exp_f32_e32 v53, v54
	v_add_f32_e32 v4, v104, v4
	v_exp_f32_e32 v54, v55
	v_add_f32_e32 v108, v133, v4
	v_add_f32_e32 v4, 0, v16
	v_exp_f32_e32 v55, v60
	v_add_f32_e32 v4, v52, v4
	v_exp_f32_e32 v60, v61
	v_add_f32_e32 v4, v53, v4
	v_exp_f32_e32 v61, v62
	v_add_f32_e32 v4, v54, v4
	v_exp_f32_e32 v62, v63
	v_add_f32_e32 v4, v4, v55
	v_exp_f32_e32 v5, v100
	v_add_f32_e32 v4, v60, v4
	v_exp_f32_e32 v6, v101
	v_add_f32_e32 v4, v61, v4
	v_exp_f32_e32 v7, v102
	v_add_f32_e32 v4, v62, v4
	v_exp_f32_e32 v63, v103
	v_add_f32_e32 v4, v4, v5
	v_exp_f32_e32 v8, v8
	v_add_f32_e32 v4, v6, v4
	v_exp_f32_e32 v9, v9
	v_add_f32_e32 v4, v7, v4
	v_exp_f32_e32 v10, v10
	v_add_f32_e32 v4, v63, v4
	v_exp_f32_e32 v11, v11
	v_add_f32_e32 v4, v4, v8
	v_add_f32_e32 v4, v9, v4
	v_add_f32_e32 v4, v10, v4
	v_add_f32_e32 v4, v11, v4
	v_add_f32_e32 v109, v132, v4
	v_cvt_pk_bf16_f32 v4, v5, v6
	v_cvt_pk_bf16_f32 v5, v7, v63
	v_cvt_pk_bf16_f32 v6, v8, v9
	v_cvt_pk_bf16_f32 v7, v10, v11
	v_cvt_pk_bf16_f32 v8, v16, v52
	v_cvt_pk_bf16_f32 v9, v53, v54
	v_cvt_pk_bf16_f32 v10, v55, v60
	v_cvt_pk_bf16_f32 v11, v61, v62
	v_cvt_pk_bf16_f32 v60, v57, v58
	v_cvt_pk_bf16_f32 v61, v59, v72
	v_cvt_pk_bf16_f32 v62, v73, v74
	v_cvt_pk_bf16_f32 v63, v75, v104
	v_cvt_pk_bf16_f32 v12, v12, v13
	v_cvt_pk_bf16_f32 v13, v14, v15
	v_cvt_pk_bf16_f32 v14, v17, v18
	v_cvt_pk_bf16_f32 v15, v19, v56
	s_setprio 1
	ds_read_b128 v[16:19], v156 offset:20480
	s_waitcnt lgkmcnt(0)
	v_mfma_f32_16x16x32_bf16 v[40:43], v[16:19], v[12:15], v[40:43]
	v_mfma_f32_16x16x32_bf16 v[16:19], v[16:19], v[8:11], v[20:23]
	s_nop 2
	ds_read_b128 v[20:23], v156 offset:23040
	s_waitcnt lgkmcnt(0)
	v_mfma_f32_16x16x32_bf16 v[48:51], v[20:23], v[12:15], v[48:51]
	v_mfma_f32_16x16x32_bf16 v[20:23], v[20:23], v[8:11], v[24:27]
	s_nop 2
	ds_read_b128 v[24:27], v156 offset:25600
	s_waitcnt lgkmcnt(0)
	v_mfma_f32_16x16x32_bf16 v[52:55], v[24:27], v[12:15], v[68:71]
	v_mfma_f32_16x16x32_bf16 v[24:27], v[24:27], v[8:11], v[28:31]
	s_nop 2
	ds_read_b128 v[28:31], v156 offset:28160
	s_waitcnt lgkmcnt(0)
	v_mfma_f32_16x16x32_bf16 v[68:71], v[28:31], v[12:15], v[76:79]
	v_mfma_f32_16x16x32_bf16 v[72:75], v[28:31], v[8:11], v[32:35]
	ds_read_b128 v[28:31], v156 offset:30720
	s_waitcnt lgkmcnt(0)
	v_mfma_f32_16x16x32_bf16 v[76:79], v[28:31], v[12:15], v[80:83]
	v_mfma_f32_16x16x32_bf16 v[80:83], v[28:31], v[8:11], v[36:39]
	ds_read_b128 v[28:31], v156 offset:33280
	s_waitcnt lgkmcnt(0)
	v_mfma_f32_16x16x32_bf16 v[84:87], v[28:31], v[12:15], v[84:87]
	v_mfma_f32_16x16x32_bf16 v[100:103], v[28:31], v[8:11], v[44:47]
	ds_read_b128 v[28:31], v156 offset:35840
	s_waitcnt lgkmcnt(0)
	v_mfma_f32_16x16x32_bf16 v[88:91], v[28:31], v[12:15], v[88:91]
	v_mfma_f32_16x16x32_bf16 v[104:107], v[28:31], v[8:11], v[64:67]
	ds_read_b128 v[28:31], v156 offset:38400
	s_waitcnt lgkmcnt(0)
	v_mfma_f32_16x16x32_bf16 v[92:95], v[28:31], v[8:11], v[92:95]
	ds_read_b128 v[8:11], v156 offset:20544
	s_waitcnt lgkmcnt(0)
	v_mfma_f32_16x16x32_bf16 v[64:67], v[8:11], v[60:63], v[40:43]
	v_mfma_f32_16x16x32_bf16 v[32:35], v[8:11], v[4:7], v[16:19]
	ds_read_b128 v[8:11], v156 offset:23104
	v_mfma_f32_16x16x32_bf16 v[96:99], v[28:31], v[12:15], v[96:99]
	s_waitcnt lgkmcnt(0)
	v_mfma_f32_16x16x32_bf16 v[56:59], v[8:11], v[60:63], v[48:51]
	v_mfma_f32_16x16x32_bf16 v[28:31], v[8:11], v[4:7], v[20:23]
	ds_read_b128 v[8:11], v156 offset:25664
	s_waitcnt lgkmcnt(0)
	v_mfma_f32_16x16x32_bf16 v[52:55], v[8:11], v[60:63], v[52:55]
	v_mfma_f32_16x16x32_bf16 v[24:27], v[8:11], v[4:7], v[24:27]
	ds_read_b128 v[8:11], v156 offset:28224
	s_waitcnt lgkmcnt(0)
	v_mfma_f32_16x16x32_bf16 v[36:39], v[8:11], v[60:63], v[68:71]
	s_nop 2
	ds_read_b128 v[68:71], v156 offset:38464
	v_mfma_f32_16x16x32_bf16 v[20:23], v[8:11], v[4:7], v[72:75]
	ds_read_b128 v[8:11], v156 offset:30784
	s_waitcnt lgkmcnt(0)
	v_mfma_f32_16x16x32_bf16 v[40:43], v[8:11], v[60:63], v[76:79]
	v_mfma_f32_16x16x32_bf16 v[16:19], v[8:11], v[4:7], v[80:83]
	ds_read_b128 v[8:11], v156 offset:33344
	s_waitcnt lgkmcnt(0)
	v_mfma_f32_16x16x32_bf16 v[44:47], v[8:11], v[60:63], v[84:87]
	v_mfma_f32_16x16x32_bf16 v[12:15], v[8:11], v[4:7], v[100:103]
	ds_read_b128 v[8:11], v156 offset:35904
	s_waitcnt lgkmcnt(0)
	v_mfma_f32_16x16x32_bf16 v[48:51], v[8:11], v[60:63], v[88:91]
	v_mfma_f32_16x16x32_bf16 v[8:11], v[8:11], v[4:7], v[104:107]
	v_mfma_f32_16x16x32_bf16 v[60:63], v[68:71], v[60:63], v[96:99]
	v_mfma_f32_16x16x32_bf16 v[4:7], v[68:71], v[4:7], v[92:95]
	s_setprio 0
	v_cmp_lt_i32_e32 vcc, v173, v174
	s_barrier
; __device__ __forceinline__ void attn_diff32(const bf16_t* __restrict__ Qp, const bf16_t* __restrict__ Kp,
;                                             const bf16_t* __restrict__ Vtp, int ntiles, float negM,
;                                             f32x4 (&o)[2][8], float (&l)[2], char* smem) {
;     ...
; #pragma unroll
;   for (int qt = 0; qt < 2; ++qt) {
;     l[qt] += __shfl_xor(l[qt], 16);
;     l[qt] += __shfl_xor(l[qt], 32);
;   }
; __device__ __forceinline__ void phase_attn0(const Params& P, char* smem) {
;     ...
;       if (cmap == 1) {
; #pragma unroll
;         for (int qt = 0; qt < 2; ++qt) {
;           const float i1 = lam / l2[qt];
; #pragma unroll
;           for (int dt = 0; dt < 8; ++dt)
;             *(f32x4*)(xch + (size_t)((qg * 32 + qt * 16 + l15) * 128 + dt * 16 + quad * 4)) = o2[qt][dt] * i1;
;         }
;       }
	s_nop 0
	v_cndmask_b32_e32 v68, v172, v173, vcc
	v_cmp_lt_i32_e32 vcc, v175, v174
	v_lshlrev_b32_e32 v84, 2, v68
	s_nop 0
	v_cndmask_b32_e32 v68, v172, v175, vcc
	v_lshlrev_b32_e32 v85, 2, v68
	ds_bpermute_b32 v68, v84, v108
	s_waitcnt lgkmcnt(0)
	v_add_f32_e32 v68, v108, v68
	ds_bpermute_b32 v69, v85, v68
	s_waitcnt lgkmcnt(0)
	v_add_f32_e32 v74, v68, v69
	ds_bpermute_b32 v68, v84, v109
	s_waitcnt lgkmcnt(0)
	v_add_f32_e32 v68, v109, v68
	ds_bpermute_b32 v69, v85, v68
	s_waitcnt lgkmcnt(0)
	v_add_f32_e32 v86, v68, v69
	s_and_saveexec_b64 s[18:19], s[6:7]
	s_cbranch_execz .LBB0_330
	v_div_scale_f32 v68, s[2:3], v74, v74, v142
	v_rcp_f32_e32 v69, v68
	s_nop 0
	v_fma_f32 v70, -v68, v69, 1.0
	v_fmac_f32_e32 v69, v70, v69
	v_div_scale_f32 v70, vcc, v142, v74, v142
	v_mul_f32_e32 v71, v70, v69
	v_fma_f32 v72, -v68, v71, v70
	v_fmac_f32_e32 v71, v72, v69
	v_fma_f32 v68, -v68, v71, v70
	v_div_fmas_f32 v68, v68, v69, v71
	v_div_fixup_f32 v72, v68, v74, v142
	v_pk_mul_f32 v[70:71], v[66:67], v[72:73] op_sel_hi:[1,0]
	v_pk_mul_f32 v[68:69], v[64:65], v[72:73] op_sel_hi:[1,0]
	ds_write_b128 v169, v[68:71]
	v_pk_mul_f32 v[70:71], v[58:59], v[72:73] op_sel_hi:[1,0]
	v_pk_mul_f32 v[68:69], v[56:57], v[72:73] op_sel_hi:[1,0]
	ds_write_b128 v169, v[68:71] offset:64
	v_pk_mul_f32 v[70:71], v[54:55], v[72:73] op_sel_hi:[1,0]
	v_pk_mul_f32 v[68:69], v[52:53], v[72:73] op_sel_hi:[1,0]
	ds_write_b128 v169, v[68:71] offset:128
	v_pk_mul_f32 v[70:71], v[38:39], v[72:73] op_sel_hi:[1,0]
	v_pk_mul_f32 v[68:69], v[36:37], v[72:73] op_sel_hi:[1,0]
	ds_write_b128 v169, v[68:71] offset:192
	v_pk_mul_f32 v[70:71], v[42:43], v[72:73] op_sel_hi:[1,0]
	v_pk_mul_f32 v[68:69], v[40:41], v[72:73] op_sel_hi:[1,0]
	ds_write_b128 v169, v[68:71] offset:256
	v_pk_mul_f32 v[70:71], v[46:47], v[72:73] op_sel_hi:[1,0]
	v_pk_mul_f32 v[68:69], v[44:45], v[72:73] op_sel_hi:[1,0]
	ds_write_b128 v169, v[68:71] offset:320
	v_pk_mul_f32 v[70:71], v[50:51], v[72:73] op_sel_hi:[1,0]
	v_pk_mul_f32 v[68:69], v[48:49], v[72:73] op_sel_hi:[1,0]
	ds_write_b128 v169, v[68:71] offset:384
	v_pk_mul_f32 v[70:71], v[62:63], v[72:73] op_sel_hi:[1,0]
	v_pk_mul_f32 v[68:69], v[60:61], v[72:73] op_sel_hi:[1,0]
	ds_write_b128 v169, v[68:71] offset:448
	v_div_scale_f32 v68, s[2:3], v86, v86, v142
	v_rcp_f32_e32 v69, v68
	s_nop 0
	v_fma_f32 v70, -v68, v69, 1.0
	v_fmac_f32_e32 v69, v70, v69
	v_div_scale_f32 v70, vcc, v142, v86, v142
	v_mul_f32_e32 v71, v70, v69
	v_fma_f32 v72, -v68, v71, v70
	v_fmac_f32_e32 v71, v72, v69
	v_fma_f32 v68, -v68, v71, v70
	v_div_fmas_f32 v68, v68, v69, v71
	v_div_fixup_f32 v72, v68, v86, v142
	v_pk_mul_f32 v[70:71], v[34:35], v[72:73] op_sel_hi:[1,0]
	v_pk_mul_f32 v[68:69], v[32:33], v[72:73] op_sel_hi:[1,0]
	ds_write_b128 v169, v[68:71] offset:8192
	v_pk_mul_f32 v[70:71], v[30:31], v[72:73] op_sel_hi:[1,0]
	v_pk_mul_f32 v[68:69], v[28:29], v[72:73] op_sel_hi:[1,0]
	ds_write_b128 v169, v[68:71] offset:8256
	v_pk_mul_f32 v[70:71], v[26:27], v[72:73] op_sel_hi:[1,0]
	v_pk_mul_f32 v[68:69], v[24:25], v[72:73] op_sel_hi:[1,0]
	ds_write_b128 v169, v[68:71] offset:8320
	v_pk_mul_f32 v[70:71], v[22:23], v[72:73] op_sel_hi:[1,0]
	v_pk_mul_f32 v[68:69], v[20:21], v[72:73] op_sel_hi:[1,0]
	ds_write_b128 v169, v[68:71] offset:8384
	v_pk_mul_f32 v[70:71], v[18:19], v[72:73] op_sel_hi:[1,0]
	v_pk_mul_f32 v[68:69], v[16:17], v[72:73] op_sel_hi:[1,0]
	ds_write_b128 v169, v[68:71] offset:8448
	v_pk_mul_f32 v[70:71], v[14:15], v[72:73] op_sel_hi:[1,0]
	v_pk_mul_f32 v[68:69], v[12:13], v[72:73] op_sel_hi:[1,0]
	ds_write_b128 v169, v[68:71] offset:8512
	v_pk_mul_f32 v[70:71], v[10:11], v[72:73] op_sel_hi:[1,0]
	v_pk_mul_f32 v[68:69], v[8:9], v[72:73] op_sel_hi:[1,0]
	ds_write_b128 v169, v[68:71] offset:8576
	v_pk_mul_f32 v[70:71], v[6:7], v[72:73] op_sel_hi:[1,0]
	v_pk_mul_f32 v[68:69], v[4:5], v[72:73] op_sel_hi:[1,0]
	ds_write_b128 v169, v[68:71] offset:8640

; #define LAS __attribute__((address_space(3)))
; __global__ void __launch_bounds__(256, 2) fwd_mega(Params P) {
;   extern __shared__ __attribute__((aligned(16))) char smem[];
;   __shared__ uint4 xb_words;
;   cg::grid_group grid = cg::this_grid();
;   if (threadIdx.x == 0) xb_words = make_uint4(0u, 0u, 0u, 0u);
;   __syncthreads();
;   XcdBarrier xb = xcd_barrier_post((unsigned*)(P.ws + OFF_BAR), (volatile LAS unsigned*)&xb_words);
;   run_all<0>(P, smem, grid, xb);
; }
	.amdhsa_kernel _Z8fwd_mega6Params
		.amdhsa_group_segment_fixed_size 16
		.amdhsa_private_segment_fixed_size 0
		.amdhsa_kernarg_size 560
		.amdhsa_user_sgpr_count 2
		.amdhsa_user_sgpr_dispatch_ptr 0
		.amdhsa_user_sgpr_queue_ptr 0
		.amdhsa_user_sgpr_kernarg_segment_ptr 1
		.amdhsa_user_sgpr_dispatch_id 0
		.amdhsa_user_sgpr_kernarg_preload_length 0
		.amdhsa_user_sgpr_kernarg_preload_offset 0
		.amdhsa_user_sgpr_private_segment_size 0
		.amdhsa_uses_dynamic_stack 0
		.amdhsa_enable_private_segment 0
		.amdhsa_system_sgpr_workgroup_id_x 1
		.amdhsa_system_sgpr_workgroup_id_y 0
		.amdhsa_system_sgpr_workgroup_id_z 0
		.amdhsa_system_sgpr_workgroup_info 0
		.amdhsa_system_vgpr_workitem_id 2
		.amdhsa_next_free_vgpr 254
		.amdhsa_next_free_sgpr 100
		.amdhsa_accum_offset 256
		.amdhsa_reserve_vcc 1
		.amdhsa_float_round_mode_32 0
		.amdhsa_float_round_mode_16_64 0
		.amdhsa_float_denorm_mode_32 3
		.amdhsa_float_denorm_mode_16_64 3
		.amdhsa_dx10_clamp 1
		.amdhsa_ieee_mode 1
		.amdhsa_fp16_overflow 0
		.amdhsa_tg_split 0
		.amdhsa_exception_fp_ieee_invalid_op 0
		.amdhsa_exception_fp_denorm_src 0
		.amdhsa_exception_fp_ieee_div_zero 0
		.amdhsa_exception_fp_ieee_overflow 0
		.amdhsa_exception_fp_ieee_underflow 0
		.amdhsa_exception_fp_ieee_inexact 0
		.amdhsa_exception_int_div_zero 0
	.end_amdhsa_kernel

; #define LAS __attribute__((address_space(3)))
; __global__ void __launch_bounds__(256, 2) fwd_mega(Params P) {
;   extern __shared__ __attribute__((aligned(16))) char smem[];
;   __shared__ uint4 xb_words;
;   cg::grid_group grid = cg::this_grid();
;   if (threadIdx.x == 0) xb_words = make_uint4(0u, 0u, 0u, 0u);
;   __syncthreads();
;   XcdBarrier xb = xcd_barrier_post((unsigned*)(P.ws + OFF_BAR), (volatile LAS unsigned*)&xb_words);
;   run_all<0>(P, smem, grid, xb);
; }
amdhsa.kernels:
  - .agpr_count:     0
    .args:
      - .offset:         0
        .size:           304
        .value_kind:     by_value
      - .offset:         304
        .size:           4
        .value_kind:     hidden_block_count_x
      - .offset:         308
        .size:           4
        .value_kind:     hidden_block_count_y
      - .offset:         312
        .size:           4
        .value_kind:     hidden_block_count_z
      - .offset:         316
        .size:           2
        .value_kind:     hidden_group_size_x
      - .offset:         318
        .size:           2
        .value_kind:     hidden_group_size_y
      - .offset:         320
        .size:           2
        .value_kind:     hidden_group_size_z
      - .offset:         322
        .size:           2
        .value_kind:     hidden_remainder_x
      - .offset:         324
        .size:           2
        .value_kind:     hidden_remainder_y
      - .offset:         326
        .size:           2
        .value_kind:     hidden_remainder_z
      - .offset:         344
        .size:           8
        .value_kind:     hidden_global_offset_x
      - .offset:         352
        .size:           8
        .value_kind:     hidden_global_offset_y
      - .offset:         360
        .size:           8
        .value_kind:     hidden_global_offset_z
      - .offset:         368
        .size:           2
        .value_kind:     hidden_grid_dims
      - .offset:         392
        .size:           8
        .value_kind:     hidden_multigrid_sync_arg
      - .offset:         424
        .size:           4
        .value_kind:     hidden_dynamic_lds_size
    .group_segment_fixed_size: 16
    .kernarg_segment_align: 8
    .kernarg_segment_size: 560
    .language:       OpenCL C
    .language_version:
      - 2
      - 0
    .max_flat_workgroup_size: 256
    .name:           _Z8fwd_mega6Params
    .private_segment_fixed_size: 0
    .sgpr_count:     106
    .sgpr_spill_count: 73
    .symbol:         _Z8fwd_mega6Params.kd
    .uniform_work_group_size: 1
    .uses_dynamic_stack: false
    .vgpr_count:     254
    .vgpr_spill_count: 0
    .wavefront_size: 64
